# P3 unit order flipped on alternate XCDs (FFT2 first) to overlap memory-bound FFT2 with attention
# speedup vs baseline: 1.0932x; 1.0022x over previous
.LBB0_296:
	s_or_b64 exec, exec, s[0:1]
	s_waitcnt lgkmcnt(0)
	v_lshlrev_b32_e32 v0, 2, v190
	s_barrier
	global_load_dword v1, v0, s[20:21]
	global_load_dword v2, v0, s[22:23]
	v_mbcnt_hi_u32_b32 v0, -1, v218
	v_and_b32_e32 v3, 64, v0
	v_xor_b32_e32 v4, 1, v0
	v_add_u32_e32 v3, 64, v3
	v_cmp_lt_i32_e32 vcc, v4, v3
	v_xor_b32_e32 v5, 2, v0
	v_xor_b32_e32 v6, 4, v0
	v_cndmask_b32_e32 v4, v0, v4, vcc
	v_lshlrev_b32_e32 v142, 2, v4
	v_cmp_lt_i32_e32 vcc, v5, v3
	v_xor_b32_e32 v7, 8, v0
	v_xor_b32_e32 v8, 16, v0
	v_cndmask_b32_e32 v5, v0, v5, vcc
	v_lshlrev_b32_e32 v143, 2, v5
	v_cmp_lt_i32_e32 vcc, v6, v3
	v_xor_b32_e32 v9, 32, v0
	s_add_u32 s0, s42, 0x11800000
	v_cndmask_b32_e32 v6, v0, v6, vcc
	v_lshlrev_b32_e32 v144, 2, v6
	v_cmp_lt_i32_e32 vcc, v7, v3
	s_addc_u32 s1, s43, 0
	v_mov_b32_e32 v99, 0
	v_cndmask_b32_e32 v6, v0, v7, vcc
	v_lshlrev_b32_e32 v145, 2, v6
	v_cmp_lt_i32_e32 vcc, v8, v3
	s_mov_b32 s17, 0
	s_cmpk_lt_i32 s75, 0xc00
	v_cndmask_b32_e32 v6, v0, v8, vcc
	v_lshlrev_b32_e32 v146, 2, v6
	v_cmp_lt_i32_e32 vcc, v9, v3
	s_waitcnt vmcnt(1)
	v_and_b32_e32 v4, 0x7fffffff, v1
	s_waitcnt vmcnt(0)
	v_and_b32_e32 v10, 0x7fffffff, v2
	ds_bpermute_b32 v4, v142, v4
	ds_bpermute_b32 v10, v142, v10
	v_max_f32_e64 v1, |v1|, |v1|
	v_max_f32_e64 v2, |v2|, |v2|
	v_cndmask_b32_e32 v0, v0, v9, vcc
	s_waitcnt lgkmcnt(1)
	v_max_f32_e32 v4, v4, v4
	s_waitcnt lgkmcnt(0)
	v_max_f32_e32 v5, v10, v10
	v_max_f32_e32 v1, v1, v4
	v_max_f32_e32 v2, v2, v5
	ds_bpermute_b32 v4, v143, v1
	ds_bpermute_b32 v5, v143, v2
	v_lshlrev_b32_e32 v147, 2, v0
	s_waitcnt lgkmcnt(1)
	v_max_f32_e32 v4, v4, v4
	s_waitcnt lgkmcnt(0)
	v_max_f32_e32 v5, v5, v5
	v_max_f32_e32 v1, v1, v4
	v_max_f32_e32 v2, v2, v5
	ds_bpermute_b32 v4, v144, v1
	ds_bpermute_b32 v5, v144, v2
	s_waitcnt lgkmcnt(1)
	v_max_f32_e32 v4, v4, v4
	s_waitcnt lgkmcnt(0)
	v_max_f32_e32 v5, v5, v5
	v_max_f32_e32 v1, v1, v4
	v_max_f32_e32 v2, v2, v5
	ds_bpermute_b32 v4, v145, v1
	ds_bpermute_b32 v5, v145, v2
	s_waitcnt lgkmcnt(1)
	v_max_f32_e32 v4, v4, v4
	s_waitcnt lgkmcnt(0)
	v_max_f32_e32 v5, v5, v5
	v_max_f32_e32 v1, v1, v4
	v_max_f32_e32 v2, v2, v5
	ds_bpermute_b32 v4, v146, v1
	ds_bpermute_b32 v5, v146, v2
	s_waitcnt lgkmcnt(1)
	v_max_f32_e32 v0, v4, v4
	s_waitcnt lgkmcnt(0)
	v_max_f32_e32 v3, v5, v5
	v_max_f32_e32 v0, v1, v0
	v_max_f32_e32 v1, v2, v3
	ds_bpermute_b32 v2, v147, v0
	ds_bpermute_b32 v3, v147, v1
	s_waitcnt lgkmcnt(1)
	v_max_f32_e32 v2, v2, v2
	s_waitcnt lgkmcnt(0)
	v_max_f32_e32 v3, v3, v3
	v_max_f32_e32 v0, v0, v2
	v_max_f32_e32 v1, v1, v3
	v_mul_f32_e32 v0, 0x4138aa3b, v0
	v_mul_f32_e32 v0, v0, v1
	s_nop 0
	v_readfirstlane_b32 s2, v0
	s_cbranch_scc0 .LBB0_320
	v_mov_b32_e32 v0, 0x42200000
	s_lshl_b32 s4, s74, 12
	v_lshrrev_b32_e32 v148, 3, v191
	v_cmp_nlt_f32_e64 s[2:3], s2, v0
	s_lshl_b32 s18, s74, 5
	s_add_i32 s4, s4, 0
	s_mov_b32 s19, s17
	v_xor_b32_e32 v0, v148, v191
	s_add_i32 s11, s4, 0x10000
	s_lshl_b64 s[4:5], s[18:19], 2
	v_lshlrev_b32_e32 v0, 4, v0
	s_add_u32 s4, s26, s4
	v_and_b32_e32 v0, 48, v0
	v_lshlrev_b32_e32 v2, 7, v148
	v_xor_b32_e32 v3, v212, v191
	s_movk_i32 s6, 0x70
	s_addc_u32 s5, s27, s5
	v_lshlrev_b32_e32 v98, 4, v197
	v_add_u32_e32 v4, s11, v0
	v_and_b32_e32 v0, 4, v191
	v_and_or_b32 v2, v3, s6, v2
	v_bfe_u32 v3, v191, 1, 3
	v_bitop3_b32 v14, v197, v219, 7 bitop3:0x78
	v_lshl_add_u64 v[100:101], s[4:5], 0, v[98:99]
	v_cmp_eq_u32_e64 s[4:5], 0, v0
	v_and_b32_e32 v0, 56, v220
	v_readlane_b32 s8, v254, 22
	v_lshlrev_b32_e32 v156, 4, v14
	v_bitop3_b32 v14, v197, v3, 2 bitop3:0x36
	v_add_u32_e32 v150, 0, v2
	v_lshlrev_b32_e32 v2, 7, v189
	v_lshlrev_b32_e32 v98, 1, v0
	v_readlane_b32 s9, v254, 23
	v_lshlrev_b32_e32 v157, 4, v14
	v_bitop3_b32 v14, v197, v3, 4 bitop3:0x36
	v_bitop3_b32 v3, v197, v3, 6 bitop3:0x36
	v_add_u32_e32 v151, 0, v2
	v_add_u32_e32 v5, s11, v2
	v_and_b32_e32 v2, 15, v191
	v_lshl_add_u64 v[102:103], s[8:9], 0, v[98:99]
	v_readlane_b32 s8, v254, 5
	v_lshlrev_b32_e32 v159, 4, v3
	v_bitop3_b32 v3, v197, v191, 15 bitop3:0x78
	v_mov_b32_e32 v195, v99
	v_readlane_b32 s9, v254, 6
	v_lshlrev_b32_e32 v158, 4, v14
	v_lshlrev_b32_e32 v14, 3, v3
	v_bitop3_b32 v3, v197, v2, 2 bitop3:0x36
	v_lshl_add_u64 v[106:107], s[8:9], 0, v[194:195]
	s_mov_b64 s[8:9], 0x1000
	v_lshlrev_b32_e32 v15, 3, v3
	v_bitop3_b32 v3, v197, v2, 4 bitop3:0x36
	v_lshl_add_u64 v[108:109], v[106:107], 0, s[8:9]
	s_mov_b64 s[8:9], 0x1400
	v_lshlrev_b32_e32 v16, 3, v3
	v_bitop3_b32 v3, v197, v2, 6 bitop3:0x36
	v_lshl_add_u64 v[110:111], v[106:107], 0, s[8:9]
	s_mov_b64 s[8:9], 0x1800
	v_lshlrev_b32_e32 v17, 3, v3
	v_bitop3_b32 v3, v197, v2, 8 bitop3:0x36
	v_lshl_add_u64 v[112:113], v[106:107], 0, s[8:9]
	s_mov_b64 s[8:9], 0x1c00
	v_lshlrev_b32_e32 v18, 3, v3
	v_bitop3_b32 v3, v197, v2, 10 bitop3:0x36
	v_lshrrev_b32_e32 v152, 3, v190
	v_lshl_add_u64 v[114:115], v[106:107], 0, s[8:9]
	s_mov_b64 s[8:9], 0x2000
	v_lshlrev_b32_e32 v19, 3, v3
	v_bitop3_b32 v3, v197, v2, 12 bitop3:0x36
	v_bitop3_b32 v2, v197, v2, 14 bitop3:0x36
	v_lshl_add_u64 v[116:117], v[106:107], 0, s[8:9]
	s_mov_b64 s[8:9], 0x2400
	v_lshlrev_b32_e32 v21, 3, v2
	v_and_b32_e32 v2, 0x70, v212
	v_or_b32_e32 v160, 8, v152
	v_lshl_add_u64 v[118:119], v[106:107], 0, s[8:9]
	s_mov_b64 s[8:9], 0x2800
	v_bitop3_b32 v23, v191, v2, 48 bitop3:0x6c
	v_lshrrev_b32_e32 v2, 1, v160
	v_lshl_add_u64 v[120:121], v[106:107], 0, s[8:9]
	s_mov_b64 s[8:9], 0x2c00
	v_xor_b32_e32 v2, v2, v191
	v_lshl_add_u64 v[122:123], v[106:107], 0, s[8:9]
	s_mov_b64 s[8:9], 0x3000
	v_lshlrev_b32_e32 v2, 4, v2
	v_or_b32_e32 v162, 24, v152
	v_lshl_add_u64 v[124:125], v[106:107], 0, s[8:9]
	s_mov_b64 s[8:9], 0x3400
	v_and_b32_e32 v25, 0x70, v2
	v_lshrrev_b32_e32 v2, 1, v162
	v_lshl_add_u64 v[126:127], v[106:107], 0, s[8:9]
	s_mov_b64 s[8:9], 0x3800
	v_xor_b32_e32 v2, v2, v191
	v_and_b32_e32 v6, 8, v191
	v_lshl_add_u64 v[104:105], s[0:1], 0, v[98:99]
	v_lshl_add_u64 v[128:129], v[106:107], 0, s[8:9]
	s_mov_b64 s[8:9], 0x3c00
	v_lshlrev_b32_e32 v2, 4, v2
	v_lshlrev_b32_e32 v98, 4, v217
	v_cmp_eq_u32_e64 s[6:7], 0, v6
	v_lshl_add_u64 v[130:131], v[106:107], 0, s[8:9]
	v_bitop3_b32 v6, v197, v191, 7 bitop3:0x78
	v_bitop3_b32 v7, v197, v217, 2 bitop3:0x36
	v_bitop3_b32 v8, v197, v217, 4 bitop3:0x36
	v_bitop3_b32 v9, v197, v217, 6 bitop3:0x36
	v_or_b32_e32 v153, 16, v193
	v_or_b32_e32 v154, 32, v193
	v_or_b32_e32 v155, 48, v193
	v_lshlrev_b32_e32 v20, 3, v3
	v_or_b32_e32 v161, 16, v152
	v_and_b32_e32 v28, 0x70, v2
	v_lshl_add_u64 v[2:3], s[42:43], 0, v[98:99]
	s_mov_b64 s[8:9], 0xac00100
	v_lshl_add_u32 v1, v189, 6, s11
	v_lshlrev_b32_e32 v6, 3, v6
	v_lshlrev_b32_e32 v7, 3, v7
	v_lshlrev_b32_e32 v8, 3, v8
	v_lshlrev_b32_e32 v9, 3, v9
	v_lshlrev_b32_e32 v10, 6, v193
	v_lshlrev_b32_e32 v11, 6, v153
	v_lshlrev_b32_e32 v12, 6, v154
	v_lshlrev_b32_e32 v13, 6, v155
	v_lshl_add_u32 v22, v152, 7, s11
	v_lshl_add_u32 v24, v160, 7, s11
	v_lshl_add_u32 v26, v161, 7, s11
	v_lshl_add_u32 v27, v162, 7, s11
	v_lshl_add_u64 v[132:133], v[2:3], 0, s[8:9]
	s_mov_b64 s[8:9], 0xa008000
	v_and_b32_e32 v149, 24, v220
	v_lshl_add_u64 v[134:135], v[2:3], 0, s[8:9]
	v_add_u32_e32 v163, v1, v6
	v_add_u32_e32 v164, v1, v7
	v_add_u32_e32 v165, v1, v8
	v_add_u32_e32 v166, v1, v9
	v_add_u32_e32 v167, v4, v10
	v_add_u32_e32 v168, v4, v11
	v_add_u32_e32 v169, v4, v12
	v_add_u32_e32 v170, v4, v13
	v_lshlrev_b32_e32 v136, 1, v0
	s_movk_i32 s11, 0x4000
	s_mov_b32 s19, 0x41000000
	s_mov_b64 s[20:21], 0x80
	v_add_u32_e32 v171, v5, v14
	v_add_u32_e32 v172, v5, v15
	v_add_u32_e32 v173, v5, v16
	v_add_u32_e32 v174, v5, v17
	v_add_u32_e32 v175, v5, v18
	v_add_u32_e32 v176, v5, v19
	v_add_u32_e32 v177, v5, v20
	v_add_u32_e32 v178, v5, v21
	v_add_u32_e32 v179, v22, v23
	v_add_u32_e32 v180, v24, v25
	v_add_u32_e32 v181, v26, v23
	v_add_u32_e32 v182, v27, v28
	v_mov_b32_e32 v183, 0x3c3504f3
	v_mov_b32_e32 v184, 0x3c800000
	s_mov_b32 s28, s75
	s_mov_b32 s44, 0
	s_mov_b32 s45, s75
.Lp3_cnt:
	s_add_i32 s44, s44, 1
	s_add_i32 s45, s45, s68
	s_cmpk_lt_i32 s45, 0xc00
	s_cbranch_scc1 .Lp3_cnt
	s_cmpk_lg_i32 s68, 0x100
	s_cbranch_scc1 .Lp3_noflip
	s_and_b32 s45, s75, 32
	s_cmp_eq_u32 s45, 0
	s_cbranch_scc1 .Lp3_noflip
	s_addk_i32 s28, 0x600
.Lp3_noflip:
	s_branch .LBB0_300

.LBB0_299:
	s_add_i32 s28, s28, s68
	s_cmpk_gt_i32 s28, 0xbff
	s_cbranch_scc0 .Lp3_nowrap
	s_addk_i32 s28, 0xf400
.Lp3_nowrap:
	s_add_i32 s44, s44, -1
	s_cmp_eq_u32 s44, 0
	s_cbranch_scc1 .LBB0_320
